# final RMSNorm: weight chunks 1-3 loaded together with chunk 0 (no per-chunk vmcnt(0) behind the stores)
# baseline (speedup 1.0000x reference)
; template <int MODE> __device__ __forceinline__ void norm_row2(const float* xa, const float* xb, const float* nw, const float* sca, const float* sha, const float* scb, const float* shb, ...
;     const f32x4* pa = (const f32x4*)xa + lane; const f32x4* pb = (const f32x4*)xb + lane;
;     f32x4 va[4], vb[4]; float s0 = 0.f, s1 = 0.f;
; #pragma unroll
;     for (int j = 0; j < 4; ++j) { va[j] = pa[64 * j]; vb[j] = pb[64 * j]; }
; #pragma unroll
;     for (int j = 0; j < 4; ++j) { s0 += (va[j].x * va[j].x + va[j].y * va[j].y) + (va[j].z * va[j].z + va[j].w * va[j].w); s1 += (vb[j].x * vb[j].x + vb[j].y * vb[j].y) + (vb[j].z * vb[j].z + vb[j].w * vb[j].w); }
; #pragma unroll
;     for (int o = 1; o < 64; o <<= 1) { s0 += __shfl_xor(s0, o); s1 += __shfl_xor(s1, o); }
;     const float r0 = 1.f / sqrtf(s0 * (1.f / D) + eps), r1 = 1.f / sqrtf(s1 * (1.f / D) + eps);
; __global__ void __launch_bounds__(512, 2) hymba_fwd(Args a) {
;     ...
;         for (int row = gw; row < TT; row += 2 * NGW) { const int rb_ = row + NGW;
;             if (rb_ < TT) norm_row2<1>(a.out + (size_t)row * D, a.out + (size_t)rb_ * D, a.in[29], nullptr, nullptr, nullptr, nullptr, nullptr, nullptr, a.out + (size_t)row * D, a.out + (size_t)rb_ * D, 1e-6f, lane);
.LBB0_1240:
	s_andn2_b64 vcc, exec, s[0:1]
	s_cbranch_vccnz .LBB0_1237
	global_load_dwordx4 v[24:27], v40, s[6:7]
	global_load_dwordx4 v[16:19], v40, s[6:7] offset:1024
	global_load_dwordx4 v[4:7], v40, s[6:7] offset:3072
	global_load_dwordx4 v[8:11], v40, s[6:7] offset:2048
	s_ashr_i32 s5, s4, 31
	s_lshl_b64 s[8:9], s[4:5], 12
	v_lshl_add_u64 v[36:37], v[34:35], 0, s[8:9]
	global_load_dwordx4 v[28:31], v[36:37], off
	global_load_dwordx4 v[20:23], v[36:37], off offset:1024
	s_waitcnt lgkmcnt(0)
	global_load_dwordx4 v[0:3], v[36:37], off offset:3072
	global_load_dwordx4 v[12:15], v[36:37], off offset:2048
	v_cmp_lt_i32_e32 vcc, v43, v42
	s_waitcnt vmcnt(0)
	v_pk_mul_f32 v[52:53], v[24:25], v[24:25]
	v_cndmask_b32_e32 v49, v41, v43, vcc
	v_cmp_lt_i32_e32 vcc, v44, v42
	v_pk_mul_f32 v[54:55], v[18:19], v[18:19]
	v_pk_mul_f32 v[56:57], v[16:17], v[16:17]
	v_cndmask_b32_e32 v50, v41, v44, vcc
	v_lshlrev_b32_e32 v70, 2, v50
	v_pk_mul_f32 v[50:51], v[26:27], v[26:27]
	v_mul_f32_e32 v61, v6, v6
	v_mul_f32_e32 v58, v9, v9
	v_mul_f32_e32 v60, v11, v11
	v_pk_mov_b32 v[62:63], v[52:53], v[50:51] op_sel:[1,0]
	v_mov_b32_e32 v53, v51
	v_pk_mov_b32 v[50:51], v[56:57], v[54:55] op_sel:[1,0]
	v_mov_b32_e32 v57, v55
	v_mul_f32_e32 v64, v7, v7
	v_pk_fma_f32 v[54:55], v[8:9], v[8:9], v[58:59] op_sel_hi:[1,1,0]
	v_pk_fma_f32 v[58:59], v[10:11], v[10:11], v[60:61] op_sel_hi:[1,1,0]
	v_pk_add_f32 v[52:53], v[62:63], v[52:53]
	v_pk_add_f32 v[50:51], v[50:51], v[56:57]
	v_cmp_lt_i32_e32 vcc, v45, v42
	v_mul_f32_e32 v71, v4, v4
	v_mul_f32_e32 v72, v5, v5
	v_mov_b32_e32 v55, v61
	v_mov_b32_e32 v59, v64
	v_pk_add_f32 v[52:53], v[52:53], v[52:53] op_sel:[0,1] op_sel_hi:[1,0]
	v_pk_add_f32 v[50:51], v[50:51], v[50:51] op_sel:[0,1] op_sel_hi:[1,0]
	v_cndmask_b32_e32 v67, v41, v45, vcc
	v_pk_mul_f32 v[56:57], v[30:31], v[30:31]
	v_pk_mul_f32 v[60:61], v[28:29], v[28:29]
	v_pk_mul_f32 v[62:63], v[22:23], v[22:23]
	v_pk_mul_f32 v[64:65], v[20:21], v[20:21]
	v_pk_add_f32 v[54:55], v[54:55], v[58:59]
	v_mul_f32_e32 v58, v13, v13
	v_mul_f32_e32 v66, v15, v15
	v_mov_b32_e32 v53, v71
	v_mov_b32_e32 v51, v72
	v_mul_f32_e32 v75, v2, v2
	v_mul_f32_e32 v76, v3, v3
	v_pk_mov_b32 v[68:69], v[60:61], v[56:57] op_sel:[1,0]
	v_mov_b32_e32 v61, v57
	v_pk_mov_b32 v[56:57], v[64:65], v[62:63] op_sel:[1,0]
	v_mov_b32_e32 v65, v63
	v_pk_fma_f32 v[58:59], v[12:13], v[12:13], v[58:59] op_sel_hi:[1,1,0]
	v_pk_fma_f32 v[62:63], v[14:15], v[14:15], v[66:67] op_sel_hi:[1,1,0]
	v_pk_add_f32 v[50:51], v[52:53], v[50:51]
	v_pk_add_f32 v[56:57], v[56:57], v[64:65]
	v_mov_b32_e32 v59, v75
	v_mov_b32_e32 v63, v76
	v_pk_add_f32 v[50:51], v[50:51], v[54:55]
	v_lshlrev_b32_e32 v49, 2, v49
	v_pk_add_f32 v[54:55], v[56:57], v[56:57] op_sel:[0,1] op_sel_hi:[1,0]
	v_pk_add_f32 v[56:57], v[58:59], v[62:63]
	v_add_f32_e32 v58, v50, v51
	v_pk_add_f32 v[60:61], v[68:69], v[60:61]
	ds_bpermute_b32 v59, v49, v58
	v_mul_f32_e32 v73, v0, v0
	v_mul_f32_e32 v74, v1, v1
	v_pk_add_f32 v[52:53], v[60:61], v[60:61] op_sel:[0,1] op_sel_hi:[1,0]
	v_mov_b32_e32 v55, v74
	v_mov_b32_e32 v53, v73
	v_pk_add_f32 v[50:51], v[52:53], v[54:55]
	v_lshlrev_b32_e32 v54, 2, v67
	v_pk_add_f32 v[50:51], v[50:51], v[56:57]
	v_cmp_lt_i32_e32 vcc, v46, v42
	v_add_f32_e32 v50, v50, v51
	s_waitcnt lgkmcnt(0)
	v_add_f32_e32 v51, v58, v59
	ds_bpermute_b32 v49, v49, v50
	ds_bpermute_b32 v52, v70, v51
	v_cndmask_b32_e32 v53, v41, v46, vcc
	v_lshlrev_b32_e32 v56, 2, v53
	v_cmp_lt_i32_e32 vcc, v47, v42
	s_waitcnt lgkmcnt(1)
	v_add_f32_e32 v49, v50, v49
	s_waitcnt lgkmcnt(0)
	v_add_f32_e32 v51, v51, v52
	ds_bpermute_b32 v50, v70, v49
	ds_bpermute_b32 v52, v54, v51
	v_cndmask_b32_e32 v55, v41, v47, vcc
	v_lshlrev_b32_e32 v55, 2, v55
	v_cmp_lt_i32_e32 vcc, v48, v42
	s_waitcnt lgkmcnt(1)
	v_add_f32_e32 v49, v49, v50
	s_waitcnt lgkmcnt(0)
	v_add_f32_e32 v57, v51, v52
	global_load_dwordx4 v[50:53], v[32:33], off
	global_load_dwordx4 v[244:247], v[32:33], off offset:1024
	global_load_dwordx4 v[248:251], v[32:33], off offset:2048
	global_load_dwordx4 v[252:255], v[32:33], off offset:3072
	ds_bpermute_b32 v54, v54, v49
	ds_bpermute_b32 v58, v56, v57
	s_waitcnt lgkmcnt(1)
	v_add_f32_e32 v49, v49, v54
	ds_bpermute_b32 v54, v56, v49
	s_waitcnt lgkmcnt(1)
	v_add_f32_e32 v56, v57, v58
	ds_bpermute_b32 v57, v55, v56
	v_cndmask_b32_e32 v58, v41, v48, vcc
	s_waitcnt lgkmcnt(1)
; __device__ __forceinline__ unsigned pk2(float lo, float hi) { return f2bf(lo) | (f2bf(hi) << 16); }
; template <int MODE> __device__ __forceinline__ void norm_row2(const float* xa, const float* xb, const float* nw, const float* sca, const float* sha, const float* scb, const float* shb, ...
;     ...
;     const float r0 = 1.f / sqrtf(s0 * (1.f / D) + eps), r1 = 1.f / sqrtf(s1 * (1.f / D) + eps);
; #pragma unroll
;     for (int j = 0; j < 4; ++j) { const f32x4 w = ((const f32x4*)nw)[64 * j + lane]; f32x4 ya = va[j] * r0 * w, yb = vb[j] * r1 * w;
;         if (MODE == 0) { const f32x4 ca = ((const f32x4*)sca)[64 * j + lane], ha = ((const f32x4*)sha)[64 * j + lane], cb = ((const f32x4*)scb)[64 * j + lane], hb = ((const f32x4*)shb)[64 * j + lane];
;             ya = ya * (ca + 1.f) + ha; yb = yb * (cb + 1.f) + hb;
;             u32x2 o; o.x = pk2(ya.x, ya.y); o.y = pk2(ya.z, ya.w); ((u32x2*)oa)[64 * j + lane] = o; o.x = pk2(yb.x, yb.y); o.y = pk2(yb.z, yb.w); ((u32x2*)ob)[64 * j + lane] = o; }
;         else { ((f32x4*)fa_)[64 * j + lane] = ya; ((f32x4*)fb_)[64 * j + lane] = yb; } }
	v_add_f32_e32 v49, v49, v54
	ds_bpermute_b32 v54, v55, v49
	v_lshlrev_b32_e32 v55, 2, v58
	s_waitcnt lgkmcnt(1)
	v_add_f32_e32 v56, v56, v57
	ds_bpermute_b32 v57, v55, v56
	s_waitcnt lgkmcnt(1)
	v_add_f32_e32 v49, v49, v54
	ds_bpermute_b32 v54, v55, v49
	s_waitcnt lgkmcnt(1)
	v_add_f32_e32 v55, v56, v57
	v_fmamk_f32 v55, v55, 0x3a800000, v38
	v_mul_f32_e32 v56, 0x4f800000, v55
	v_cmp_gt_f32_e32 vcc, s10, v55
	s_waitcnt lgkmcnt(0)
	v_add_f32_e32 v49, v49, v54
	v_fmamk_f32 v49, v49, 0x3a800000, v38
	v_cndmask_b32_e32 v54, v55, v56, vcc
	v_sqrt_f32_e32 v55, v54
	v_mul_f32_e32 v56, 0x4f800000, v49
	v_cmp_gt_f32_e64 s[0:1], s10, v49
	v_add_u32_e32 v57, -1, v55
	v_add_u32_e32 v58, 1, v55
	v_fma_f32 v59, -v57, v55, v54
	v_fma_f32 v60, -v58, v55, v54
	v_cmp_ge_f32_e64 s[2:3], 0, v59
	v_cndmask_b32_e64 v49, v49, v56, s[0:1]
	v_sqrt_f32_e32 v56, v49
	v_cndmask_b32_e64 v55, v55, v57, s[2:3]
	v_cmp_lt_f32_e64 s[2:3], 0, v60
	v_add_u32_e32 v57, -1, v56
	s_nop 0
	v_cndmask_b32_e64 v55, v55, v58, s[2:3]
	v_mul_f32_e32 v59, 0x37800000, v55
	v_cndmask_b32_e32 v55, v55, v59, vcc
	v_cmp_class_f32_e32 vcc, v54, v39
	v_fma_f32 v60, -v57, v56, v49
	v_add_u32_e32 v58, 1, v56
	v_cndmask_b32_e32 v54, v55, v54, vcc
	v_div_scale_f32 v55, s[2:3], v54, v54, 1.0
	v_rcp_f32_e32 v59, v55
	v_cmp_ge_f32_e32 vcc, 0, v60
	v_fma_f32 v61, -v58, v56, v49
	v_cmp_lt_f32_e64 s[2:3], 0, v61
	v_fma_f32 v60, -v55, v59, 1.0
	v_cndmask_b32_e32 v56, v56, v57, vcc
	v_div_scale_f32 v57, vcc, 1.0, v54, 1.0
	v_fmac_f32_e32 v59, v60, v59
	v_mul_f32_e32 v60, v57, v59
	v_fma_f32 v62, -v55, v60, v57
	v_fmac_f32_e32 v60, v62, v59
	v_cndmask_b32_e64 v56, v56, v58, s[2:3]
	v_fma_f32 v55, -v55, v60, v57
	v_mul_f32_e32 v57, 0x37800000, v56
	v_cndmask_b32_e64 v56, v56, v57, s[0:1]
	v_cmp_class_f32_e64 s[0:1], v49, v39
	v_div_fmas_f32 v55, v55, v59, v60
	v_div_fixup_f32 v54, v55, v54, 1.0
	v_cndmask_b32_e64 v49, v56, v49, s[0:1]
	v_div_scale_f32 v56, s[0:1], v49, v49, 1.0
	v_rcp_f32_e32 v57, v56
	s_nop 0
	v_fma_f32 v55, -v56, v57, 1.0
	v_fmac_f32_e32 v57, v55, v57
	v_div_scale_f32 v55, vcc, 1.0, v49, 1.0
	v_mul_f32_e32 v58, v55, v57
	v_fma_f32 v59, -v56, v58, v55
	v_fmac_f32_e32 v58, v59, v57
	v_fma_f32 v55, -v56, v58, v55
	v_div_fmas_f32 v55, v55, v57, v58
	v_div_fixup_f32 v56, v55, v49, 1.0
	v_pk_mul_f32 v[24:25], v[24:25], v[54:55] op_sel_hi:[1,0]
	v_pk_mul_f32 v[26:27], v[26:27], v[54:55] op_sel_hi:[1,0]
	s_waitcnt vmcnt(0)
	v_pk_mul_f32 v[24:25], v[50:51], v[24:25]
	v_pk_mul_f32 v[26:27], v[52:53], v[26:27]
	v_pk_mul_f32 v[28:29], v[28:29], v[56:57] op_sel_hi:[1,0]
	v_pk_mul_f32 v[30:31], v[30:31], v[56:57] op_sel_hi:[1,0]
	v_pk_mul_f32 v[28:29], v[50:51], v[28:29]
	v_pk_mul_f32 v[30:31], v[52:53], v[30:31]
	global_store_dwordx4 v40, v[24:27], s[6:7]
	global_store_dwordx4 v[36:37], v[28:31], off
	v_pk_mul_f32 v[18:19], v[18:19], v[54:55] op_sel_hi:[1,0]
	v_pk_mul_f32 v[16:17], v[16:17], v[54:55] op_sel_hi:[1,0]
	v_pk_mul_f32 v[22:23], v[22:23], v[56:57] op_sel_hi:[1,0]
	v_pk_mul_f32 v[20:21], v[20:21], v[56:57] op_sel_hi:[1,0]
	v_pk_mul_f32 v[10:11], v[10:11], v[54:55] op_sel_hi:[1,0]
	v_pk_mul_f32 v[8:9], v[8:9], v[54:55] op_sel_hi:[1,0]
	v_pk_mul_f32 v[14:15], v[14:15], v[56:57] op_sel_hi:[1,0]
	v_pk_mul_f32 v[12:13], v[12:13], v[56:57] op_sel_hi:[1,0]
	v_pk_mul_f32 v[6:7], v[6:7], v[54:55] op_sel_hi:[1,0]
	v_pk_mul_f32 v[4:5], v[4:5], v[54:55] op_sel_hi:[1,0]
	v_pk_mul_f32 v[2:3], v[2:3], v[56:57] op_sel_hi:[1,0]
	v_pk_mul_f32 v[0:1], v[0:1], v[56:57] op_sel_hi:[1,0]
	v_pk_mul_f32 v[16:17], v[244:245], v[16:17]
	v_pk_mul_f32 v[18:19], v[246:247], v[18:19]
	v_pk_mul_f32 v[20:21], v[244:245], v[20:21]
	v_pk_mul_f32 v[22:23], v[246:247], v[22:23]
	global_store_dwordx4 v40, v[16:19], s[6:7] offset:1024
	global_store_dwordx4 v[36:37], v[20:23], off offset:1024
	v_pk_mul_f32 v[8:9], v[248:249], v[8:9]
	v_pk_mul_f32 v[10:11], v[250:251], v[10:11]
	v_pk_mul_f32 v[12:13], v[248:249], v[12:13]
	v_pk_mul_f32 v[14:15], v[250:251], v[14:15]
	global_store_dwordx4 v40, v[8:11], s[6:7] offset:2048
	global_store_dwordx4 v[36:37], v[12:15], off offset:2048
	v_pk_mul_f32 v[4:5], v[4:5], v[252:253]
	v_pk_mul_f32 v[6:7], v[6:7], v[254:255]
	v_pk_mul_f32 v[0:1], v[0:1], v[252:253]
	v_pk_mul_f32 v[2:3], v[2:3], v[254:255]
	global_store_dwordx4 v40, v[4:7], s[6:7] offset:3072
	s_branch .LBB0_1237
